# gmlp task start: redundant s_waitcnt vmcnt(0) (waited on the preceding bias task's stores) removed
# baseline (speedup 1.0000x reference)
.Lbias_ret4:
	s_and_b32 s2, s33, -2
	s_add_i32 s2, s2, s90
	s_and_b32 s38, s2, 3
	s_or_b32 s28, s38, s75
	v_mov_b32_e32 v0, v229
	s_ashr_i32 s29, s28, 31
	s_lshl_b64 s[0:1], s[28:29], 16
	v_and_b32_e32 v116, 15, v0
	v_readlane_b32 s40, v253, 3
	v_ashrrev_i32_e32 v6, 6, v0
	v_bfe_u32 v117, v0, 4, 2
	v_readlane_b32 s41, v253, 4
	s_add_u32 s0, s40, s0
	v_lshlrev_b32_e32 v2, 7, v116
	s_addc_u32 s1, s41, s1
	v_lshlrev_b32_e32 v200, 5, v117
	v_lshl_or_b32 v2, v6, 12, v2
	s_waitcnt lgkmcnt(0)
	v_lshl_add_u64 v[0:1], s[0:1], 0, v[200:201]
	v_ashrrev_i32_e32 v3, 31, v2
	v_lshl_add_u64 v[4:5], v[2:3], 2, v[0:1]
	v_or_b32_e32 v2, 0x800, v2
	v_ashrrev_i32_e32 v3, 31, v2
	s_lshl_b32 s3, s2, 5
	v_lshlrev_b32_e32 v104, 5, v6
	v_lshlrev_b32_e32 v105, 2, v117
	v_lshl_add_u64 v[0:1], v[2:3], 2, v[0:1]
	s_and_b32 s0, s3, 0xffffff80
	v_or_b32_e32 v2, v105, v104
	v_add_u32_e32 v88, s0, v2
	v_mov_b64_e32 v[72:73], s[20:21]
	global_load_dwordx4 v[56:59], v[4:5], off offset:16
	global_load_dwordx4 v[60:63], v[4:5], off
	global_load_dwordx4 v[64:67], v[0:1], off offset:16
	global_load_dwordx4 v[68:71], v[0:1], off
	global_load_dwordx4 v[44:47], v[4:5], off offset:144
	global_load_dwordx4 v[52:55], v[4:5], off offset:128
	global_load_dwordx4 v[40:43], v[0:1], off offset:144
	global_load_dwordx4 v[48:51], v[0:1], off offset:128
	global_load_dwordx4 v[28:31], v[4:5], off offset:272
	global_load_dwordx4 v[36:39], v[4:5], off offset:256
	global_load_dwordx4 v[24:27], v[0:1], off offset:272
	global_load_dwordx4 v[32:35], v[0:1], off offset:256
	global_load_dwordx4 v[12:15], v[4:5], off offset:400
	global_load_dwordx4 v[20:23], v[4:5], off offset:384
	global_load_dwordx4 v[8:11], v[0:1], off offset:400
	global_load_dwordx4 v[16:19], v[0:1], off offset:384
	v_lshl_add_u32 v0, s28, 7, v2
	v_mad_i64_i32 v[2:3], s[28:29], v88, s92, v[72:73]
	s_lshl_b32 s94, s38, 7
	v_lshl_add_u64 v[2:3], v[2:3], 0, s[94:95]
	v_lshlrev_b32_e32 v200, 1, v116
	v_lshl_add_u64 v[74:75], v[2:3], 0, v[200:201]
	v_or_b32_e32 v2, 1, v88
	v_mad_i64_i32 v[2:3], s[28:29], v2, s92, v[72:73]
	v_lshl_add_u64 v[2:3], v[2:3], 0, s[94:95]
	v_lshl_add_u64 v[76:77], v[2:3], 0, v[200:201]
	v_or_b32_e32 v2, 2, v88
	v_or_b32_e32 v86, 18, v88
	v_mad_i64_i32 v[2:3], s[28:29], v2, s92, v[72:73]
	v_mad_i64_i32 v[86:87], s[28:29], v86, s92, v[72:73]
	v_lshl_add_u64 v[2:3], v[2:3], 0, s[94:95]
	v_lshl_add_u64 v[86:87], v[86:87], 0, s[94:95]
	v_lshl_add_u64 v[78:79], v[2:3], 0, v[200:201]
	v_or_b32_e32 v2, 3, v88
	v_or_b32_e32 v82, 16, v88
	v_or_b32_e32 v84, 17, v88
	v_lshl_add_u64 v[118:119], v[86:87], 0, v[200:201]
	v_or_b32_e32 v86, 19, v88
	v_mad_i64_i32 v[2:3], s[28:29], v2, s92, v[72:73]
	v_mad_i64_i32 v[82:83], s[28:29], v82, s92, v[72:73]
	v_mad_i64_i32 v[84:85], s[28:29], v84, s92, v[72:73]
	v_mad_i64_i32 v[72:73], s[28:29], v86, s92, v[72:73]
	v_readlane_b32 s42, v253, 5
	v_readlane_b32 s43, v253, 6
	v_ashrrev_i32_e32 v1, 31, v0
	v_lshl_add_u64 v[82:83], v[82:83], 0, s[94:95]
	v_lshl_add_u64 v[84:85], v[84:85], 0, s[94:95]
	v_lshl_add_u64 v[72:73], v[72:73], 0, s[94:95]
	s_mul_i32 s28, s0, 0x1600
	v_lshl_add_u64 v[0:1], v[0:1], 2, s[42:43]
	v_lshl_add_u64 v[2:3], v[2:3], 0, s[94:95]
	v_lshl_add_u64 v[82:83], v[82:83], 0, v[200:201]
	v_lshl_add_u64 v[84:85], v[84:85], 0, v[200:201]
	v_lshl_add_u64 v[72:73], v[72:73], 0, v[200:201]
	s_mul_hi_i32 s1, s0, 0x1600
	s_add_u32 s28, s20, s28
	v_mov_b32_e32 v124, v229
	global_load_dwordx4 v[4:7], v[0:1], off
	v_lshl_add_u64 v[80:81], v[2:3], 0, v[200:201]
	global_load_dwordx4 v[0:3], v[0:1], off offset:64
	s_addc_u32 s1, s21, s1
	global_load_ushort v115, v[74:75], off offset:1024
	global_load_ushort v114, v[74:75], off offset:1056
	global_load_ushort v113, v[74:75], off offset:1088
	global_load_ushort v112, v[74:75], off offset:1120
	global_load_ushort v111, v[76:77], off offset:1024
	global_load_ushort v110, v[76:77], off offset:1056
	global_load_ushort v109, v[76:77], off offset:1088
	global_load_ushort v108, v[76:77], off offset:1120
	global_load_ushort v107, v[78:79], off offset:1024
	global_load_ushort v106, v[78:79], off offset:1056
	global_load_ushort v103, v[78:79], off offset:1088
	global_load_ushort v102, v[78:79], off offset:1120
	global_load_ushort v101, v[80:81], off offset:1024
	global_load_ushort v100, v[80:81], off offset:1056
	global_load_ushort v99, v[80:81], off offset:1088
	global_load_ushort v98, v[80:81], off offset:1120
	global_load_ushort v97, v[82:83], off offset:1024
	global_load_ushort v96, v[82:83], off offset:1056
	global_load_ushort v95, v[82:83], off offset:1088
	global_load_ushort v94, v[82:83], off offset:1120
	global_load_ushort v93, v[84:85], off offset:1024
	global_load_ushort v92, v[84:85], off offset:1056
	global_load_ushort v91, v[84:85], off offset:1088
	global_load_ushort v90, v[84:85], off offset:1120
	global_load_ushort v89, v[118:119], off offset:1024
	global_load_ushort v88, v[118:119], off offset:1056
	global_load_ushort v87, v[118:119], off offset:1088
	global_load_ushort v86, v[118:119], off offset:1120
	s_nop 0
	global_load_ushort v85, v[72:73], off offset:1024
	global_load_ushort v84, v[72:73], off offset:1056
	global_load_ushort v83, v[72:73], off offset:1088
	global_load_ushort v82, v[72:73], off offset:1120
	s_add_u32 s28, s28, s94
	v_lshlrev_b32_e32 v72, 2, v124
	v_and_b32_e32 v125, 60, v72
	s_addc_u32 s29, s1, 0
	v_lshlrev_b32_e32 v72, 1, v125
	v_mov_b32_e32 v73, v201
	v_lshl_add_u64 v[72:73], s[28:29], 0, v[72:73]
	v_ashrrev_i32_e32 v74, 4, v124
	v_mad_i64_i32 v[118:119], s[28:29], v74, s92, v[72:73]
	global_load_dwordx2 v[118:119], v[118:119], off offset:1536
	v_add_u32_e32 v126, 0x100, v124
	v_ashrrev_i32_e32 v74, 4, v126
	v_add_u32_e32 v127, 0x200, v124
	v_mad_i64_i32 v[120:121], s[28:29], v74, s92, v[72:73]
	v_ashrrev_i32_e32 v74, 4, v127
	v_add_u32_e32 v128, 0x300, v124
	v_mad_i64_i32 v[122:123], s[28:29], v74, s92, v[72:73]
	v_ashrrev_i32_e32 v74, 4, v128
	v_add_u32_e32 v129, 0x400, v124
	v_mad_i64_i32 v[80:81], s[28:29], v74, s92, v[72:73]
	v_ashrrev_i32_e32 v74, 4, v129
	v_add_u32_e32 v130, 0x500, v124
	v_mad_i64_i32 v[78:79], s[28:29], v74, s92, v[72:73]
	v_ashrrev_i32_e32 v74, 4, v130
	v_add_u32_e32 v131, 0x600, v124
	v_add_u32_e32 v132, 0x700, v124
	v_mad_i64_i32 v[76:77], s[28:29], v74, s92, v[72:73]
	v_ashrrev_i32_e32 v74, 4, v131
	v_ashrrev_i32_e32 v133, 4, v132
	v_mad_i64_i32 v[74:75], s[28:29], v74, s92, v[72:73]
	v_mad_i64_i32 v[72:73], s[28:29], v133, s92, v[72:73]
	global_load_dwordx2 v[120:121], v[120:121], off offset:1536
	global_load_dwordx2 v[122:123], v[122:123], off offset:1536
	global_load_dwordx2 v[80:81], v[80:81], off offset:1536
	global_load_dwordx2 v[78:79], v[78:79], off offset:1536
	global_load_dwordx2 v[76:77], v[76:77], off offset:1536
	global_load_dwordx2 v[74:75], v[74:75], off offset:1536
	global_load_dwordx2 v[72:73], v[72:73], off offset:1536
	v_mov_b32_e32 v133, s69
	s_movk_i32 s1, 0x110
	v_ashrrev_i32_e32 v124, 3, v124
	v_mad_u32_u24 v125, v125, s1, v133
	v_and_b32_e32 v124, -2, v124
	v_add_u32_e32 v124, v125, v124
	s_waitcnt vmcnt(0)
	ds_write_b16 v124, v118
	ds_write_b16_d16_hi v124, v118 offset:272
	ds_write_b16 v124, v119 offset:544
	ds_write_b16_d16_hi v124, v119 offset:816
	v_ashrrev_i32_e32 v118, 3, v126
	v_and_b32_e32 v118, -2, v118
	v_add_u32_e32 v124, v125, v118
	v_cvt_pk_bf16_f32 v60, v60, v61
	v_cvt_pk_bf16_f32 v61, v62, v63
	v_cvt_pk_bf16_f32 v63, v58, v59
	v_cvt_pk_bf16_f32 v58, v64, v65
	v_mul_u32_u24_e32 v64, 0x110, v116
	v_cvt_pk_bf16_f32 v62, v56, v57
	v_cvt_pk_bf16_f32 v56, v68, v69
	v_cvt_pk_bf16_f32 v57, v70, v71
	v_cvt_pk_bf16_f32 v59, v66, v67
	s_waitcnt vmcnt(0)
	ds_write_b16 v124, v120
	ds_write_b16_d16_hi v124, v120 offset:272
	ds_write_b16 v124, v121 offset:544
	ds_write_b16_d16_hi v124, v121 offset:816
	v_ashrrev_i32_e32 v118, 3, v127
	v_and_b32_e32 v118, -2, v118
	v_add_u32_e32 v120, v125, v118
	v_cvt_pk_bf16_f32 v52, v52, v53
	v_cvt_pk_bf16_f32 v53, v54, v55
	v_cvt_pk_bf16_f32 v54, v44, v45
	v_cvt_pk_bf16_f32 v55, v46, v47
	v_cvt_pk_bf16_f32 v44, v48, v49
	v_cvt_pk_bf16_f32 v45, v50, v51
	v_cvt_pk_bf16_f32 v46, v40, v41
	s_waitcnt vmcnt(0)
	ds_write_b16 v120, v122
	ds_write_b16_d16_hi v120, v122 offset:272
	ds_write_b16 v120, v123 offset:544
	ds_write_b16_d16_hi v120, v123 offset:816
	v_ashrrev_i32_e32 v118, 3, v128
	v_and_b32_e32 v118, -2, v118
	v_add_u32_e32 v118, v125, v118
	v_cvt_pk_bf16_f32 v47, v42, v43
	v_cvt_pk_bf16_f32 v36, v36, v37
	v_cvt_pk_bf16_f32 v37, v38, v39
	v_cvt_pk_bf16_f32 v38, v28, v29
	s_waitcnt vmcnt(0)
	ds_write_b16 v118, v80
	ds_write_b16_d16_hi v118, v80 offset:272
	ds_write_b16 v118, v81 offset:544
	ds_write_b16_d16_hi v118, v81 offset:816
	v_ashrrev_i32_e32 v80, 3, v129
	v_and_b32_e32 v80, -2, v80
	v_add_u32_e32 v80, v125, v80
	v_cvt_pk_bf16_f32 v39, v30, v31
	v_cvt_pk_bf16_f32 v28, v32, v33
	v_cvt_pk_bf16_f32 v29, v34, v35
	v_cvt_pk_bf16_f32 v30, v24, v25
	s_waitcnt vmcnt(0)
	ds_write_b16 v80, v78
	ds_write_b16_d16_hi v80, v78 offset:272
	ds_write_b16 v80, v79 offset:544
	ds_write_b16_d16_hi v80, v79 offset:816
	v_ashrrev_i32_e32 v78, 3, v130
	v_and_b32_e32 v78, -2, v78
	v_add_u32_e32 v78, v125, v78
	v_cvt_pk_bf16_f32 v31, v26, v27
	v_cvt_pk_bf16_f32 v20, v20, v21
	v_cvt_pk_bf16_f32 v21, v22, v23
	v_cvt_pk_bf16_f32 v22, v12, v13
	s_waitcnt vmcnt(0)
	ds_write_b16 v78, v76
	ds_write_b16_d16_hi v78, v76 offset:272
	ds_write_b16 v78, v77 offset:544
	ds_write_b16_d16_hi v78, v77 offset:816
	v_ashrrev_i32_e32 v76, 3, v131
	v_and_b32_e32 v76, -2, v76
	v_add_u32_e32 v76, v125, v76
	v_cvt_pk_bf16_f32 v23, v14, v15
	v_cvt_pk_bf16_f32 v12, v16, v17
	v_cvt_pk_bf16_f32 v13, v18, v19
	v_cvt_pk_bf16_f32 v14, v8, v9
	s_waitcnt vmcnt(0)
	ds_write_b16 v76, v74
	ds_write_b16_d16_hi v76, v74 offset:272
	ds_write_b16 v76, v75 offset:544
	ds_write_b16_d16_hi v76, v75 offset:816
	v_ashrrev_i32_e32 v74, 3, v132
	v_and_b32_e32 v74, -2, v74
	v_add_u32_e32 v74, v125, v74
	v_cvt_pk_bf16_f32 v15, v10, v11
	v_readlane_b32 s48, v253, 11
	v_readlane_b32 s49, v253, 12
	v_readlane_b32 s50, v253, 13
	s_waitcnt vmcnt(0)
	ds_write_b16 v74, v72
	ds_write_b16_d16_hi v74, v72 offset:272
	ds_write_b16 v74, v73 offset:544
	ds_write_b16_d16_hi v74, v73 offset:816
	v_lshlrev_b32_e32 v72, 4, v117
	s_waitcnt lgkmcnt(0)
	s_barrier
	v_add3_u32 v80, s69, v72, v64
	ds_read_b128 v[64:67], v80
	ds_read_b128 v[68:71], v80 offset:4352
	ds_read_b128 v[72:75], v80 offset:8704
	ds_read_b128 v[76:79], v80 offset:13056
	s_waitcnt lgkmcnt(3)
	v_mfma_f32_16x16x32_bf16 v[116:119], v[60:63], v[64:67], 0
	v_readlane_b32 s51, v253, 14
	v_readlane_b32 s52, v253, 15
	v_readlane_b32 s53, v253, 16
	s_waitcnt lgkmcnt(2)
	v_mfma_f32_16x16x32_bf16 v[120:123], v[60:63], v[68:71], 0
	v_readlane_b32 s54, v253, 17
	v_readlane_b32 s55, v253, 18
	v_readlane_b32 s48, v254, 57
	s_waitcnt lgkmcnt(1)
	v_mfma_f32_16x16x32_bf16 v[124:127], v[60:63], v[72:75], 0
	v_readlane_b32 s60, v255, 5
	v_readlane_b32 s61, v255, 6
	v_readlane_b32 s46, v253, 9
	s_waitcnt lgkmcnt(0)
	v_mfma_f32_16x16x32_bf16 v[60:63], v[60:63], v[76:79], 0
	v_readlane_b32 s47, v253, 10
	v_readlane_b32 s44, v253, 7
	v_readlane_b32 s45, v253, 8
	v_mfma_f32_16x16x32_bf16 v[64:67], v[56:59], v[64:67], 0
	v_readlane_b32 s49, v254, 58
	v_readlane_b32 s50, v254, 59
	v_readlane_b32 s51, v254, 60
	v_mfma_f32_16x16x32_bf16 v[68:71], v[56:59], v[68:71], 0
	v_readlane_b32 s52, v254, 61
	v_readlane_b32 s53, v254, 62
	v_readlane_b32 s54, v254, 63
	v_mfma_f32_16x16x32_bf16 v[72:75], v[56:59], v[72:75], 0
	v_readlane_b32 s55, v255, 0
	v_readlane_b32 s56, v255, 1
	v_readlane_b32 s57, v255, 2
	v_mfma_f32_16x16x32_bf16 v[56:59], v[56:59], v[76:79], 0
	ds_read_b128 v[40:43], v80 offset:64
	ds_read_b128 v[48:51], v80 offset:4416
	ds_read_b128 v[76:79], v80 offset:8768
	ds_read_b128 v[128:131], v80 offset:13120
	v_readlane_b32 s58, v255, 3
	v_readlane_b32 s59, v255, 4
	s_waitcnt lgkmcnt(3)
	v_mfma_f32_16x16x32_bf16 v[116:119], v[52:55], v[40:43], v[116:119]
	v_readlane_b32 s62, v255, 7
	v_readlane_b32 s63, v255, 8
	s_waitcnt lgkmcnt(2)
	v_mfma_f32_16x16x32_bf16 v[120:123], v[52:55], v[48:51], v[120:123]
	s_waitcnt lgkmcnt(1)
	v_mfma_f32_16x16x32_bf16 v[124:127], v[52:55], v[76:79], v[124:127]
	s_waitcnt lgkmcnt(0)
	v_mfma_f32_16x16x32_bf16 v[52:55], v[52:55], v[128:131], v[60:63]
	v_mfma_f32_16x16x32_bf16 v[40:43], v[44:47], v[40:43], v[64:67]
	v_mfma_f32_16x16x32_bf16 v[48:51], v[44:47], v[48:51], v[68:71]
	v_mfma_f32_16x16x32_bf16 v[60:63], v[44:47], v[76:79], v[72:75]
	v_mfma_f32_16x16x32_bf16 v[44:47], v[44:47], v[128:131], v[56:59]
	ds_read_b128 v[24:27], v80 offset:128
	ds_read_b128 v[32:35], v80 offset:4480
	s_nop 0
	ds_read_b128 v[56:59], v80 offset:8832
	ds_read_b128 v[64:67], v80 offset:13184
	s_waitcnt lgkmcnt(3)
	v_mfma_f32_16x16x32_bf16 v[68:71], v[36:39], v[24:27], v[116:119]
	s_waitcnt lgkmcnt(2)
	v_mfma_f32_16x16x32_bf16 v[72:75], v[36:39], v[32:35], v[120:123]
	v_mfma_f32_16x16x32_bf16 v[24:27], v[28:31], v[24:27], v[40:43]
	v_mfma_f32_16x16x32_bf16 v[32:35], v[28:31], v[32:35], v[48:51]
	s_waitcnt lgkmcnt(1)
	v_mfma_f32_16x16x32_bf16 v[40:43], v[28:31], v[56:59], v[60:63]
	s_waitcnt lgkmcnt(0)
	v_mfma_f32_16x16x32_bf16 v[28:31], v[28:31], v[64:67], v[44:47]
	ds_read_b128 v[8:11], v80 offset:192
	ds_read_b128 v[16:19], v80 offset:4544
	s_nop 0
	ds_read_b128 v[44:47], v80 offset:8896
	ds_read_b128 v[48:51], v80 offset:13248
	v_mfma_f32_16x16x32_bf16 v[76:79], v[36:39], v[56:59], v[124:127]
	v_mfma_f32_16x16x32_bf16 v[36:39], v[36:39], v[64:67], v[52:55]
	s_waitcnt lgkmcnt(3)
	v_mfma_f32_16x16x32_bf16 v[52:55], v[20:23], v[8:11], v[68:71]
	s_waitcnt lgkmcnt(2)
	v_mfma_f32_16x16x32_bf16 v[56:59], v[20:23], v[16:19], v[72:75]
	v_mfma_f32_16x16x32_bf16 v[8:11], v[12:15], v[8:11], v[24:27]
	v_mfma_f32_16x16x32_bf16 v[16:19], v[12:15], v[16:19], v[32:35]
	s_waitcnt lgkmcnt(1)
	v_mfma_f32_16x16x32_bf16 v[24:27], v[12:15], v[44:47], v[40:43]
	s_nop 1
	v_add_f32_e32 v32, v4, v52
	s_waitcnt lgkmcnt(0)
	v_mfma_f32_16x16x32_bf16 v[12:15], v[12:15], v[48:51], v[28:31]
	s_nop 2
	v_add_u32_e32 v28, s0, v104
	v_or_b32_e32 v28, v28, v105
	s_add_u32 s0, s22, s94
	v_ashrrev_i32_e32 v29, 31, v28
	s_addc_u32 s1, s23, 0
	v_lshlrev_b64 v[30:31], 11, v[28:29]
	v_lshlrev_b32_e32 v29, 16, v115
	v_lshl_add_u64 v[30:31], s[0:1], 0, v[30:31]
	v_mul_f32_e32 v29, v32, v29
	v_mfma_f32_16x16x32_bf16 v[60:63], v[20:23], v[44:47], v[76:79]
	v_cvt_pk_bf16_f32 v29, v29, s0
	v_lshl_add_u64 v[30:31], v[30:31], 0, v[200:201]
	global_store_short v[30:31], v29, off offset:512
	v_lshlrev_b32_e32 v29, 16, v114
	v_add_f32_e32 v32, v4, v56
	v_mul_f32_e32 v29, v32, v29
	v_mfma_f32_16x16x32_bf16 v[20:23], v[20:23], v[48:51], v[36:39]
	v_cvt_pk_bf16_f32 v29, v29, s0
	global_store_short v[30:31], v29, off offset:544
	v_lshlrev_b32_e32 v29, 16, v113
	v_add_f32_e32 v32, v4, v60
	v_mul_f32_e32 v29, v32, v29
	v_cvt_pk_bf16_f32 v29, v29, s0
	global_store_short v[30:31], v29, off offset:576
	v_lshlrev_b32_e32 v29, 16, v112
	v_add_f32_e32 v4, v4, v20
	v_mul_f32_e32 v4, v4, v29
	v_cvt_pk_bf16_f32 v4, v4, s0
	global_store_short v[30:31], v4, off offset:608
	v_or_b32_e32 v30, 1, v28
	v_ashrrev_i32_e32 v31, 31, v30
	v_lshlrev_b64 v[30:31], 11, v[30:31]
	v_lshlrev_b32_e32 v4, 16, v111
	v_add_f32_e32 v20, v5, v53
	v_lshl_add_u64 v[30:31], s[0:1], 0, v[30:31]
	v_mul_f32_e32 v4, v20, v4
	v_cvt_pk_bf16_f32 v4, v4, s0
	v_lshl_add_u64 v[30:31], v[30:31], 0, v[200:201]
	global_store_short v[30:31], v4, off offset:512
	v_lshlrev_b32_e32 v4, 16, v110
	v_add_f32_e32 v20, v5, v57
	v_mul_f32_e32 v4, v20, v4
	v_cvt_pk_bf16_f32 v4, v4, s0
	global_store_short v[30:31], v4, off offset:544
	v_lshlrev_b32_e32 v4, 16, v109
	v_add_f32_e32 v20, v5, v61
	v_mul_f32_e32 v4, v20, v4
	v_cvt_pk_bf16_f32 v4, v4, s0
	global_store_short v[30:31], v4, off offset:576
	v_lshlrev_b32_e32 v4, 16, v108
	v_add_f32_e32 v5, v5, v21
	v_mul_f32_e32 v4, v5, v4
	v_cvt_pk_bf16_f32 v4, v4, s0
	global_store_short v[30:31], v4, off offset:608
	v_or_b32_e32 v4, 2, v28
	v_ashrrev_i32_e32 v5, 31, v4
	v_lshlrev_b64 v[4:5], 11, v[4:5]
	v_lshlrev_b32_e32 v20, 16, v107
	v_add_f32_e32 v21, v6, v54
	v_lshl_add_u64 v[4:5], s[0:1], 0, v[4:5]
	v_mul_f32_e32 v20, v21, v20
	v_cvt_pk_bf16_f32 v20, v20, s0
	v_lshl_add_u64 v[4:5], v[4:5], 0, v[200:201]
	global_store_short v[4:5], v20, off offset:512
	v_lshlrev_b32_e32 v20, 16, v106
	v_add_f32_e32 v21, v6, v58
	v_mul_f32_e32 v20, v21, v20
	v_cvt_pk_bf16_f32 v20, v20, s0
	global_store_short v[4:5], v20, off offset:544
	v_lshlrev_b32_e32 v20, 16, v103
	v_add_f32_e32 v21, v6, v62
	v_mul_f32_e32 v20, v21, v20
	v_cvt_pk_bf16_f32 v20, v20, s0
	global_store_short v[4:5], v20, off offset:576
	v_lshlrev_b32_e32 v20, 16, v102
	v_add_f32_e32 v6, v6, v22
	v_mul_f32_e32 v6, v6, v20
	v_cvt_pk_bf16_f32 v6, v6, s0
	global_store_short v[4:5], v6, off offset:608
	v_or_b32_e32 v4, 3, v28
	v_ashrrev_i32_e32 v5, 31, v4
	v_lshlrev_b64 v[4:5], 11, v[4:5]
	v_lshlrev_b32_e32 v6, 16, v101
	v_add_f32_e32 v20, v7, v55
	v_lshl_add_u64 v[4:5], s[0:1], 0, v[4:5]
	v_mul_f32_e32 v6, v20, v6
	v_cvt_pk_bf16_f32 v6, v6, s0
	v_lshl_add_u64 v[4:5], v[4:5], 0, v[200:201]
	global_store_short v[4:5], v6, off offset:512
	v_lshlrev_b32_e32 v6, 16, v100
	v_add_f32_e32 v20, v7, v59
	v_mul_f32_e32 v6, v20, v6
	v_cvt_pk_bf16_f32 v6, v6, s0
	global_store_short v[4:5], v6, off offset:544
	v_lshlrev_b32_e32 v6, 16, v99
	v_add_f32_e32 v20, v7, v63
	v_mul_f32_e32 v6, v20, v6
	v_cvt_pk_bf16_f32 v6, v6, s0
	global_store_short v[4:5], v6, off offset:576
	v_lshlrev_b32_e32 v6, 16, v98
	v_add_f32_e32 v7, v7, v23
	v_mul_f32_e32 v6, v7, v6
	v_cvt_pk_bf16_f32 v6, v6, s0
	global_store_short v[4:5], v6, off offset:608
	v_or_b32_e32 v4, 16, v28
	v_ashrrev_i32_e32 v5, 31, v4
	v_lshlrev_b64 v[4:5], 11, v[4:5]
	v_lshlrev_b32_e32 v6, 16, v97
	v_add_f32_e32 v7, v0, v8
	v_lshl_add_u64 v[4:5], s[0:1], 0, v[4:5]
	v_mul_f32_e32 v6, v7, v6
	v_cvt_pk_bf16_f32 v6, v6, s0
	v_lshl_add_u64 v[4:5], v[4:5], 0, v[200:201]
	global_store_short v[4:5], v6, off offset:512
	v_lshlrev_b32_e32 v6, 16, v96
	v_add_f32_e32 v7, v0, v16
	v_mul_f32_e32 v6, v7, v6
	v_cvt_pk_bf16_f32 v6, v6, s0
	global_store_short v[4:5], v6, off offset:544
	v_lshlrev_b32_e32 v6, 16, v95
	v_add_f32_e32 v7, v0, v24
	v_mul_f32_e32 v6, v7, v6
	v_cvt_pk_bf16_f32 v6, v6, s0
	global_store_short v[4:5], v6, off offset:576
	v_lshlrev_b32_e32 v6, 16, v94
	v_add_f32_e32 v0, v0, v12
	v_mul_f32_e32 v0, v0, v6
	v_cvt_pk_bf16_f32 v0, v0, s0
	global_store_short v[4:5], v0, off offset:608
	v_or_b32_e32 v4, 17, v28
	v_ashrrev_i32_e32 v5, 31, v4
	v_lshlrev_b64 v[4:5], 11, v[4:5]
	v_lshlrev_b32_e32 v0, 16, v93
	v_add_f32_e32 v6, v1, v9
	v_lshl_add_u64 v[4:5], s[0:1], 0, v[4:5]
	v_mul_f32_e32 v0, v6, v0
	v_cvt_pk_bf16_f32 v0, v0, s0
	v_lshl_add_u64 v[4:5], v[4:5], 0, v[200:201]
	global_store_short v[4:5], v0, off offset:512
	v_lshlrev_b32_e32 v0, 16, v92
	v_add_f32_e32 v6, v1, v17
	v_mul_f32_e32 v0, v6, v0
	v_cvt_pk_bf16_f32 v0, v0, s0
	global_store_short v[4:5], v0, off offset:544
	v_lshlrev_b32_e32 v0, 16, v91
	v_add_f32_e32 v6, v1, v25
	v_mul_f32_e32 v0, v6, v0
	v_cvt_pk_bf16_f32 v0, v0, s0
	global_store_short v[4:5], v0, off offset:576
	v_lshlrev_b32_e32 v0, 16, v90
	v_add_f32_e32 v1, v1, v13
	v_mul_f32_e32 v0, v1, v0
	v_cvt_pk_bf16_f32 v0, v0, s0
	global_store_short v[4:5], v0, off offset:608
	v_or_b32_e32 v0, 18, v28
	v_ashrrev_i32_e32 v1, 31, v0
	v_lshlrev_b64 v[0:1], 11, v[0:1]
	v_lshlrev_b32_e32 v4, 16, v89
	v_add_f32_e32 v5, v2, v10
	v_lshl_add_u64 v[0:1], s[0:1], 0, v[0:1]
	v_mul_f32_e32 v4, v5, v4
	v_cvt_pk_bf16_f32 v4, v4, s0
	v_lshl_add_u64 v[0:1], v[0:1], 0, v[200:201]
	global_store_short v[0:1], v4, off offset:512
	v_lshlrev_b32_e32 v4, 16, v88
	v_add_f32_e32 v5, v2, v18
	v_mul_f32_e32 v4, v5, v4
	v_cvt_pk_bf16_f32 v4, v4, s0
	global_store_short v[0:1], v4, off offset:544
	v_lshlrev_b32_e32 v4, 16, v87
	v_add_f32_e32 v5, v2, v26
	v_mul_f32_e32 v4, v5, v4
	v_cvt_pk_bf16_f32 v4, v4, s0
	global_store_short v[0:1], v4, off offset:576
	v_lshlrev_b32_e32 v4, 16, v86
	v_add_f32_e32 v2, v2, v14
	v_mul_f32_e32 v2, v2, v4
	v_cvt_pk_bf16_f32 v2, v2, s0
	global_store_short v[0:1], v2, off offset:608
	v_or_b32_e32 v0, 19, v28
	v_ashrrev_i32_e32 v1, 31, v0
	v_lshlrev_b64 v[0:1], 11, v[0:1]
	v_lshlrev_b32_e32 v2, 16, v85
	v_add_f32_e32 v4, v3, v11
	v_lshl_add_u64 v[0:1], s[0:1], 0, v[0:1]
	v_mul_f32_e32 v2, v4, v2
	v_cvt_pk_bf16_f32 v2, v2, s0
	v_lshl_add_u64 v[0:1], v[0:1], 0, v[200:201]
	global_store_short v[0:1], v2, off offset:512
	v_lshlrev_b32_e32 v2, 16, v84
	v_add_f32_e32 v4, v3, v19
	v_mul_f32_e32 v2, v4, v2
	v_cvt_pk_bf16_f32 v2, v2, s0
	global_store_short v[0:1], v2, off offset:544
	v_lshlrev_b32_e32 v2, 16, v83
	v_add_f32_e32 v4, v3, v27
	v_mul_f32_e32 v2, v4, v2
	v_cvt_pk_bf16_f32 v2, v2, s0
	global_store_short v[0:1], v2, off offset:576
	v_lshlrev_b32_e32 v2, 16, v82
	v_add_f32_e32 v3, v3, v15
	v_mul_f32_e32 v2, v3, v2
	v_cvt_pk_bf16_f32 v2, v2, s0
	global_store_short v[0:1], v2, off offset:608
	v_mov_b32_e32 v82, v229
	s_waitcnt lgkmcnt(0)
	s_barrier
	v_mov_b32_e32 v3, v201
	v_ashrrev_i32_e32 v88, 6, v82
	v_add_u32_e32 v0, s75, v88
	v_ashrrev_i32_e32 v1, 31, v0
	v_lshlrev_b64 v[0:1], 13, v[0:1]
	v_and_b32_e32 v87, 15, v82
	v_lshl_add_u64 v[0:1], s[60:61], 0, v[0:1]
	v_and_b32_e32 v200, 48, v82
	v_lshl_add_u64 v[0:1], v[0:1], 0, v[200:201]
	v_lshlrev_b32_e32 v2, 7, v87
	v_or_b32_e32 v12, 0x1000, v2
	v_mov_b32_e32 v13, v201
	v_or_b32_e32 v14, 0x1800, v2
	v_mov_b32_e32 v15, v201
	v_lshl_add_u64 v[32:33], v[0:1], 0, 64
	v_lshl_add_u64 v[8:9], v[0:1], 0, v[2:3]
	v_lshl_add_u64 v[4:5], v[0:1], 0, v[12:13]
	v_lshl_add_u64 v[2:3], v[0:1], 0, v[14:15]
	v_lshl_add_u64 v[0:1], v[32:33], 0, v[12:13]
	v_lshl_add_u64 v[12:13], v[32:33], 0, v[14:15]
	v_and_b32_e32 v32, 0xffffffc0, v82
	v_add_u32_e32 v32, s76, v32
	v_or_b32_e32 v32, v32, v87
	v_ashrrev_i32_e32 v33, 31, v32
	v_lshl_add_u64 v[32:33], v[32:33], 2, s[46:47]
	global_load_dwordx4 v[20:23], v[8:9], off
	global_load_dwordx4 v[16:19], v[8:9], off offset:2048
	global_load_dwordx4 v[24:27], v[4:5], off
	global_load_dwordx4 v[28:31], v[2:3], off
	s_nop 0
	global_load_dwordx4 v[4:7], v[8:9], off offset:64
	s_nop 0
	global_load_dwordx4 v[8:11], v[8:9], off offset:2112
	s_cmpk_lt_i32 s2, 0x80
	global_load_dwordx4 v[0:3], v[0:1], off
	s_mov_b32 s0, 0x7ffffc00
	global_load_dwordx4 v[12:15], v[12:13], off
	s_nop 0
	global_load_dword v86, v[32:33], off
	global_load_dword v85, v[32:33], off offset:64
	global_load_dword v84, v[32:33], off offset:128
	global_load_dword v83, v[32:33], off offset:192
	s_cselect_b32 s0, 0xffffff00, s0
	s_movk_i32 s1, 0x400
	s_cselect_b32 s40, 0x100, s1
	s_and_b32 s28, s0, s3
	v_add_u32_e32 v76, s3, v88
	v_and_b32_e32 v34, 63, v82
	v_add_u32_e32 v33, -8, v76
	s_add_i32 s29, s28, s40
	v_lshlrev_b32_e32 v89, 2, v34
	v_cmp_le_i32_e32 vcc, s28, v33
	v_cmp_gt_i32_e64 s[0:1], s29, v33
	s_and_b64 s[38:39], vcc, s[0:1]
	v_mov_b32_e32 v32, 0
	v_lshlrev_b32_e32 v80, 1, v89
	v_mov_b32_e32 v81, v201
	s_mov_b32 s94, 0x800000
	s_mov_b64 s[0:1], exec
	v_add_u32_e32 v90, -8, v76
	v_cmp_le_i32_e32 vcc, s28, v90
	v_cmp_gt_i32_e64 s[38:39], s29, v90
	v_mov_b32_e32 v96, 0
	v_mov_b32_e32 v97, 0
	v_mov_b64_e32 v[92:93], s[20:21]
	s_nop 1
	s_and_b64 s[38:39], vcc, s[38:39]
	s_and_b64 exec, s[0:1], s[38:39]
	s_cbranch_execz .Lpool_skip0
	v_mad_i64_i32 v[92:93], vcc, v90, s92, v[92:93]
	v_lshl_add_u64 v[92:93], v[92:93], 0, v[80:81]
	global_load_dwordx2 v[96:97], v[92:93], off offset:2048
